# attention item: K fragments read up front and V fragments read behind the S MFMAs (no per-MFMA LDS round trip); sv staging unrolled
# baseline (speedup 1.0000x reference)
; #define LAS __attribute__((address_space(3)))
; __device__ __forceinline__ float sigmoidf_(float x) { return __builtin_amdgcn_rcpf(1.0f + __expf(-x)); }
; __device__ __forceinline__ void p0a(Frame& F, const Args& AR) {
;     ...
;         LAS float* sv = (LAS float*)F.lds;
;         for (int i = F.tid; i < 3 * DM; i += NTHR) { const int v = i / DM, d = i % DM; const float c = v < 2 ? AR.in[I_C][v * DM + d] : AR.in[I_CCTX][d]; sv[i] = c * sigmoidf_(c); }
;         __syncthreads();
.LBB0_20:
	s_or_b64 exec, exec, s[0:1]
	v_readlane_b32 s92, v250, 50
	v_readlane_b32 s72, v250, 60
	s_movk_i32 s0, 0x1800
	v_readlane_b32 s93, v250, 51
	v_readlane_b32 s73, v250, 61
	v_readlane_b32 s74, v250, 58
	v_cmp_gt_i32_e32 vcc, s0, v1
	s_and_saveexec_b64 s[0:1], vcc
	s_cbranch_execz .LBB0_27
	v_readlane_b32 s14, v250, 4
	v_readlane_b32 s15, v250, 5
	v_readlane_b32 s18, v250, 8
	v_readlane_b32 s19, v250, 9
	v_lshlrev_b32_e32 v4, 2, v1
	v_mov_b32_e32 v5, 0
	v_lshl_add_u32 v6, v1, 2, 0
	s_mov_b64 s[4:5], 0x1000
	v_lshl_add_u64 v[8:9], s[14:15], 0, v[4:5]
	v_lshl_add_u64 v[10:11], s[18:19], 0, v[4:5]
	global_load_dword v12, v[8:9], off
	global_load_dword v13, v[8:9], off offset:2048
	v_lshl_add_u64 v[8:9], v[8:9], 0, s[4:5]
	global_load_dword v14, v[8:9], off
	global_load_dword v15, v[8:9], off offset:2048
	v_lshl_add_u64 v[8:9], v[8:9], 0, s[4:5]
	global_load_dword v16, v[8:9], off
	global_load_dword v17, v[8:9], off offset:2048
	v_lshl_add_u64 v[8:9], v[8:9], 0, s[4:5]
	global_load_dword v18, v[8:9], off
	global_load_dword v19, v[8:9], off offset:2048
	global_load_dword v20, v[10:11], off
	global_load_dword v21, v[10:11], off offset:2048
	v_lshl_add_u64 v[10:11], v[10:11], 0, s[4:5]
	global_load_dword v22, v[10:11], off
	global_load_dword v23, v[10:11], off offset:2048
	s_waitcnt vmcnt(8)
	v_mul_f32_e32 v24, 0xbfb8aa3b, v12
	v_mul_f32_e32 v25, 0xbfb8aa3b, v13
	v_mul_f32_e32 v26, 0xbfb8aa3b, v14
	v_mul_f32_e32 v27, 0xbfb8aa3b, v15
	v_exp_f32_e32 v24, v24
	v_exp_f32_e32 v25, v25
	v_exp_f32_e32 v26, v26
	v_exp_f32_e32 v27, v27
	v_add_f32_e32 v24, 1.0, v24
	v_add_f32_e32 v25, 1.0, v25
	v_add_f32_e32 v26, 1.0, v26
	v_add_f32_e32 v27, 1.0, v27
	v_rcp_f32_e32 v24, v24
	v_rcp_f32_e32 v25, v25
	v_rcp_f32_e32 v26, v26
	v_rcp_f32_e32 v27, v27
	v_mul_f32_e32 v24, v12, v24
	v_mul_f32_e32 v25, v13, v25
	v_mul_f32_e32 v26, v14, v26
	v_mul_f32_e32 v27, v15, v27
	ds_write_b32 v6, v24
	ds_write_b32 v6, v25 offset:2048
	ds_write_b32 v6, v26 offset:4096
	ds_write_b32 v6, v27 offset:6144
	s_waitcnt vmcnt(4)
	v_mul_f32_e32 v24, 0xbfb8aa3b, v16
	v_mul_f32_e32 v25, 0xbfb8aa3b, v17
	v_mul_f32_e32 v26, 0xbfb8aa3b, v18
	v_mul_f32_e32 v27, 0xbfb8aa3b, v19
	v_exp_f32_e32 v24, v24
	v_exp_f32_e32 v25, v25
	v_exp_f32_e32 v26, v26
	v_exp_f32_e32 v27, v27
	v_add_f32_e32 v24, 1.0, v24
	v_add_f32_e32 v25, 1.0, v25
	v_add_f32_e32 v26, 1.0, v26
	v_add_f32_e32 v27, 1.0, v27
	v_rcp_f32_e32 v24, v24
	v_rcp_f32_e32 v25, v25
	v_rcp_f32_e32 v26, v26
	v_rcp_f32_e32 v27, v27
	v_mul_f32_e32 v24, v16, v24
	v_mul_f32_e32 v25, v17, v25
	v_mul_f32_e32 v26, v18, v26
	v_mul_f32_e32 v27, v19, v27
	ds_write_b32 v6, v24 offset:8192
	ds_write_b32 v6, v25 offset:10240
	ds_write_b32 v6, v26 offset:12288
	ds_write_b32 v6, v27 offset:14336
	s_waitcnt vmcnt(0)
	v_mul_f32_e32 v24, 0xbfb8aa3b, v20
	v_mul_f32_e32 v25, 0xbfb8aa3b, v21
	v_mul_f32_e32 v26, 0xbfb8aa3b, v22
	v_mul_f32_e32 v27, 0xbfb8aa3b, v23
	v_exp_f32_e32 v24, v24
	v_exp_f32_e32 v25, v25
	v_exp_f32_e32 v26, v26
	v_exp_f32_e32 v27, v27
	v_add_f32_e32 v24, 1.0, v24
	v_add_f32_e32 v25, 1.0, v25
	v_add_f32_e32 v26, 1.0, v26
	v_add_f32_e32 v27, 1.0, v27
	v_rcp_f32_e32 v24, v24
	v_rcp_f32_e32 v25, v25
	v_rcp_f32_e32 v26, v26
	v_rcp_f32_e32 v27, v27
	v_mul_f32_e32 v24, v20, v24
	v_mul_f32_e32 v25, v21, v25
	v_mul_f32_e32 v26, v22, v26
	v_mul_f32_e32 v27, v23, v27
	ds_write_b32 v6, v24 offset:16384
	ds_write_b32 v6, v25 offset:18432
	ds_write_b32 v6, v26 offset:20480
	ds_write_b32 v6, v27 offset:22528

; #define LAS __attribute__((address_space(3)))
; __device__ __forceinline__ unsigned pk2(float lo, float hi) { const f32x2cv v = {lo, hi}; return __builtin_bit_cast(unsigned, __builtin_convertvector(v, bf16x2cv)); }
; __device__ __forceinline__ void attn_item_mfma(Frame& F, const Args& AR, int l, int item) {
;     ...
; #pragma unroll
;         for (int kb = 0; kb < 2; ++kb) {
; #pragma unroll
;             for (int r = 0; r < 16; ++r) st[kb][r] = 0.f;
; #pragma unroll
;             for (int ks = 0; ks < 4; ++ks) { const bf16x8v kf = *(const LAS bf16x8v*)(kb_ + (32 * kb + r32) * AT_ROW + (16 * ks + 8 * hi) * 2);
;                 st[kb] = __builtin_amdgcn_mfma_f32_32x32x16_bf16(kf, qf[ks], st[kb], 0, 0, 0); }
;         }
;     ...
;         for (int m = 0; m < 4; ++m) { const int kb = m >> 1, r0 = 8 * (m & 1); v4u pw;
;             pw.x = pk2(st[kb][r0 + 0], st[kb][r0 + 1]); pw.y = pk2(st[kb][r0 + 2], st[kb][r0 + 3]); pw.z = pk2(st[kb][r0 + 4], st[kb][r0 + 5]); pw.w = pk2(st[kb][r0 + 6], st[kb][r0 + 7]);
;             const bf16x8v pf = __builtin_bit_cast(bf16x8v, pw);
; #pragma unroll
;             for (int db = 0; db < 2; ++db) { const LAS unsigned char* vp = vb_ + (32 * db + r32) * AT_ROW + (16 * m + 4 * hi) * 2;
;                 const v2u lo = *(const LAS v2u*)vp, hh = *(const LAS v2u*)(vp + 16); const v4u w = {lo.x, lo.y, hh.x, hh.y};
;                 o[db] = __builtin_amdgcn_mfma_f32_32x32x16_bf16(__builtin_bit_cast(bf16x8v, w), pf, o[db], 0, 0, 0); } }
.LBB0_1292:
	v_add3_u32 v101, s93, v96, v109
	ds_read_b128 v[124:127], v101
	ds_read_b128 v[128:131], v101 offset:32
	ds_read_b128 v[132:135], v101 offset:64
	ds_read_b128 v[136:139], v101 offset:96
	ds_read_b128 v[140:143], v101 offset:4608
	ds_read_b128 v[144:147], v101 offset:4640
	ds_read_b128 v[150:153], v101 offset:4672
	ds_read_b128 v[154:157], v101 offset:4704
	s_add_i32 s82, s92, s84
	s_and_b64 s[78:79], s[78:79], exec
	s_cselect_b32 s86, 2, s82
	s_cmp_lt_i32 s86, 4
	s_waitcnt lgkmcnt(7)
	v_mfma_f32_32x32x16_bf16 v[50:65], v[124:127], v[66:69], 0
	s_waitcnt lgkmcnt(6)
	v_mfma_f32_32x32x16_bf16 v[50:65], v[128:131], v[70:73], v[50:65]
	s_waitcnt lgkmcnt(5)
	v_mfma_f32_32x32x16_bf16 v[50:65], v[132:135], v[74:77], v[50:65]
	s_waitcnt lgkmcnt(4)
	v_mfma_f32_32x32x16_bf16 v[50:65], v[136:139], v[78:81], v[50:65]
	s_waitcnt lgkmcnt(3)
	v_mfma_f32_32x32x16_bf16 v[34:49], v[140:143], v[66:69], 0
	s_waitcnt lgkmcnt(2)
	v_mfma_f32_32x32x16_bf16 v[34:49], v[144:147], v[70:73], v[34:49]
	s_waitcnt lgkmcnt(1)
	v_mfma_f32_32x32x16_bf16 v[34:49], v[150:153], v[74:77], v[34:49]
	s_waitcnt lgkmcnt(0)
	v_mfma_f32_32x32x16_bf16 v[34:49], v[154:157], v[78:81], v[34:49]
	v_add3_u32 v190, s93, v97, v109
	v_add_u32_e32 v191, 0x3000, v190
	v_add_u32_e32 v190, 0x2000, v190
	ds_read2_b64 v[158:161], v190 offset0:128 offset1:130
	ds_read2_b64 v[162:165], v190 offset0:132 offset1:134
	ds_read2_b64 v[166:169], v191 offset0:192 offset1:194
	ds_read2_b64 v[170:173], v191 offset0:196 offset1:198
	ds_read2_b64 v[174:177], v190 offset0:136 offset1:138
	ds_read2_b64 v[178:181], v191 offset0:200 offset1:202
	ds_read2_b64 v[182:185], v190 offset0:140 offset1:142
	ds_read2_b64 v[186:189], v191 offset0:204 offset1:206
	s_cbranch_scc1 .LBB0_1294
	s_cmp_eq_u32 s86, 4
	s_cselect_b64 s[78:79], -1, 0
	s_cbranch_execz .LBB0_1295
	s_branch .LBB0_1296

; #define LAS __attribute__((address_space(3)))
; __device__ __forceinline__ unsigned pk2(float lo, float hi) { const f32x2cv v = {lo, hi}; return __builtin_bit_cast(unsigned, __builtin_convertvector(v, bf16x2cv)); }
; __device__ __forceinline__ void attn_item_mfma(Frame& F, const Args& AR, int l, int item) {
;     ...
;         float ps = 0.f;
; #pragma unroll
;         for (int kb = 0; kb < 2; ++kb)
; #pragma unroll
;             for (int r = 0; r < 16; ++r) { st[kb][r] = __builtin_amdgcn_exp2f(st[kb][r] - mnew); ps += st[kb][r]; }
;         lsum = lsum * corr + ps;
;         if (__builtin_amdgcn_ballot_w64(corr != 1.0f) != 0ull) {
; #pragma unroll
;             for (int db = 0; db < 2; ++db)
; #pragma unroll
;                 for (int r = 0; r < 16; ++r) o[db][r] *= corr; }
; #pragma unroll
;         for (int m = 0; m < 4; ++m) { const int kb = m >> 1, r0 = 8 * (m & 1); v4u pw;
;             pw.x = pk2(st[kb][r0 + 0], st[kb][r0 + 1]); pw.y = pk2(st[kb][r0 + 2], st[kb][r0 + 3]); pw.z = pk2(st[kb][r0 + 4], st[kb][r0 + 5]); pw.w = pk2(st[kb][r0 + 6], st[kb][r0 + 7]);
;             const bf16x8v pf = __builtin_bit_cast(bf16x8v, pw);
; #pragma unroll
;             for (int db = 0; db < 2; ++db) { const LAS unsigned char* vp = vb_ + (32 * db + r32) * AT_ROW + (16 * m + 4 * hi) * 2;
;                 const v2u lo = *(const LAS v2u*)vp, hh = *(const LAS v2u*)(vp + 16); const v4u w = {lo.x, lo.y, hh.x, hh.y};
;                 o[db] = __builtin_amdgcn_mfma_f32_32x32x16_bf16(__builtin_bit_cast(bf16x8v, w), pf, o[db], 0, 0, 0); } }
.LBB0_1300:
	v_sub_f32_e32 v50, v50, v101
	v_exp_f32_e32 v50, v50
	v_sub_f32_e32 v51, v51, v101
	v_exp_f32_e32 v51, v51
	v_sub_f32_e32 v52, v52, v101
	v_exp_f32_e32 v52, v52
	v_sub_f32_e32 v53, v53, v101
	v_exp_f32_e32 v53, v53
	v_sub_f32_e32 v54, v54, v101
	v_add_f32_e32 v99, 0, v50
	v_exp_f32_e32 v54, v54
	v_sub_f32_e32 v55, v55, v101
	v_add_f32_e32 v99, v51, v99
	v_exp_f32_e32 v55, v55
	v_sub_f32_e32 v56, v56, v101
	v_add_f32_e32 v99, v52, v99
	v_exp_f32_e32 v56, v56
	v_sub_f32_e32 v57, v57, v101
	v_add_f32_e32 v99, v53, v99
	v_exp_f32_e32 v57, v57
	v_sub_f32_e32 v58, v58, v101
	v_add_f32_e32 v99, v54, v99
	v_exp_f32_e32 v58, v58
	v_sub_f32_e32 v59, v59, v101
	v_add_f32_e32 v99, v55, v99
	v_exp_f32_e32 v59, v59
	v_sub_f32_e32 v60, v60, v101
	v_add_f32_e32 v99, v56, v99
	v_exp_f32_e32 v60, v60
	v_sub_f32_e32 v61, v61, v101
	v_add_f32_e32 v99, v57, v99
	v_exp_f32_e32 v61, v61
	v_sub_f32_e32 v62, v62, v101
	v_add_f32_e32 v99, v58, v99
	v_exp_f32_e32 v62, v62
	v_sub_f32_e32 v63, v63, v101
	v_add_f32_e32 v99, v59, v99
	v_exp_f32_e32 v63, v63
	v_sub_f32_e32 v64, v64, v101
	v_add_f32_e32 v99, v60, v99
	v_exp_f32_e32 v64, v64
	v_sub_f32_e32 v65, v65, v101
	v_add_f32_e32 v99, v61, v99
	v_exp_f32_e32 v65, v65
	v_sub_f32_e32 v34, v34, v101
	v_add_f32_e32 v99, v62, v99
	v_exp_f32_e32 v112, v34
	v_add_f32_e32 v99, v63, v99
	v_add_f32_e32 v99, v64, v99
	v_add_f32_e32 v99, v65, v99
	v_sub_f32_e32 v36, v36, v101
	v_add_f32_e32 v34, v112, v99
	v_exp_f32_e32 v99, v36
	v_sub_f32_e32 v36, v37, v101
	v_exp_f32_e32 v113, v36
	v_sub_f32_e32 v36, v38, v101
	v_exp_f32_e32 v114, v36
	v_sub_f32_e32 v36, v39, v101
	v_exp_f32_e32 v115, v36
	v_sub_f32_e32 v36, v40, v101
	v_exp_f32_e32 v116, v36
	v_sub_f32_e32 v36, v41, v101
	v_exp_f32_e32 v117, v36
	v_sub_f32_e32 v36, v42, v101
	v_exp_f32_e32 v118, v36
	v_sub_f32_e32 v36, v43, v101
	v_exp_f32_e32 v119, v36
	v_sub_f32_e32 v36, v44, v101
	v_exp_f32_e32 v120, v36
	v_sub_f32_e32 v36, v45, v101
	v_exp_f32_e32 v121, v36
	v_sub_f32_e32 v36, v46, v101
	v_exp_f32_e32 v122, v36
	v_sub_f32_e32 v36, v47, v101
	v_exp_f32_e32 v123, v36
	v_sub_f32_e32 v36, v48, v101
	v_exp_f32_e32 v48, v36
	v_sub_f32_e32 v36, v49, v101
	v_exp_f32_e32 v49, v36
	v_cvt_pk_bf16_f32 v36, v50, v51
	v_add3_u32 v50, s93, v97, v109
	v_add_u32_e32 v51, 0x2000, v50
	s_nop 0
	s_nop 0
	v_cvt_pk_bf16_f32 v37, v52, v53
	v_cvt_pk_bf16_f32 v38, v54, v55
	v_cvt_pk_bf16_f32 v39, v56, v57
	v_add_u32_e32 v50, 0x3000, v50
	v_sub_f32_e32 v35, v35, v101
	s_waitcnt lgkmcnt(1)
	v_mfma_f32_32x32x16_bf16 v[18:33], v[158:161], v[36:39], v[18:33]
	s_nop 0
	v_exp_f32_e32 v35, v35
	s_add_i32 s84, s84, 1
	s_add_i32 s90, s90, 64
	s_add_i32 s88, s88, 64
	v_add_f32_e32 v34, v35, v34
	v_add_f32_e32 v34, v99, v34
	s_waitcnt lgkmcnt(0)
	v_mfma_f32_32x32x16_bf16 v[2:17], v[166:169], v[36:39], v[2:17]
	s_nop 0
	v_cvt_pk_bf16_f32 v36, v58, v59
	v_cvt_pk_bf16_f32 v37, v60, v61
	v_cvt_pk_bf16_f32 v38, v62, v63
	v_cvt_pk_bf16_f32 v39, v64, v65
	v_add_f32_e32 v34, v113, v34
	v_add_f32_e32 v34, v114, v34
	s_waitcnt lgkmcnt(0)
	v_mfma_f32_32x32x16_bf16 v[2:17], v[170:173], v[36:39], v[2:17]
	s_nop 0
	v_add_f32_e32 v34, v115, v34
	v_add_f32_e32 v34, v116, v34
	v_add_f32_e32 v34, v117, v34
	v_add_f32_e32 v34, v118, v34
	v_add_f32_e32 v34, v119, v34
	v_add_f32_e32 v34, v120, v34
	v_mfma_f32_32x32x16_bf16 v[18:33], v[162:165], v[36:39], v[18:33]
	v_cvt_pk_bf16_f32 v36, v112, v35
	v_cvt_pk_bf16_f32 v37, v99, v113
	v_cvt_pk_bf16_f32 v38, v114, v115
	v_cvt_pk_bf16_f32 v39, v116, v117
	v_add_f32_e32 v34, v121, v34
	v_add_f32_e32 v34, v122, v34
	v_add_f32_e32 v34, v123, v34
	s_waitcnt lgkmcnt(0)
	v_mfma_f32_32x32x16_bf16 v[18:33], v[174:177], v[36:39], v[18:33]
	s_nop 0
	v_add_f32_e32 v34, v48, v34
	v_add_f32_e32 v34, v49, v34
	v_fmac_f32_e32 v34, v111, v102
	s_cmp_lg_u32 s91, s84
	s_waitcnt lgkmcnt(0)
	v_mfma_f32_32x32x16_bf16 v[2:17], v[178:181], v[36:39], v[2:17]
	s_nop 0
	v_cvt_pk_bf16_f32 v36, v118, v119
	v_cvt_pk_bf16_f32 v37, v120, v121
	v_cvt_pk_bf16_f32 v38, v122, v123
	v_cvt_pk_bf16_f32 v39, v48, v49
	s_waitcnt lgkmcnt(0)
	s_nop 0
	v_mfma_f32_32x32x16_bf16 v[18:33], v[182:185], v[36:39], v[18:33]
	s_nop 0
	s_waitcnt lgkmcnt(0)
	v_mfma_f32_32x32x16_bf16 v[2:17], v[186:189], v[36:39], v[2:17]
	s_cbranch_scc0 .LBB0_1305
	v_mov_b32_e32 v111, v34
	v_mov_b32_e32 v99, v101
	s_branch .LBB0_1284
